# attn-C: row-max chain trimmed (no self-max canonicalisation), rescale factor/new max computed only on the rare path (common path: alpha=1, m unchanged)
# baseline (speedup 1.0000x reference)
; #define SBAR() __builtin_amdgcn_sched_barrier(0)
; #define SLOAD(i, k0) do { sv0[i] = *(const bf16x8*)(&Vh[(long)((k0) + sr) * LDK + sc]); sv1[i] = *(const bf16x8*)(&Vh[(long)((k0) + 32 + sr) * LDK + sc]); \
;     sk0[i] = *(const bf16x8*)(&Kh[(long)((k0) + sr) * LDK + sc]); sk1[i] = *(const bf16x8*)(&Kh[(long)((k0) + 32 + sr) * LDK + sc]); } while (0)
; __device__ __forceinline__ void finishSM(f32x16& p0, f32x16& p1, float alpha, float& l_reg, bf16x8& pa0, bf16x8& pa1, bf16x8& pa2, bf16x8& pa3) {
; #pragma unroll
;     for (int r = 0; r < 16; ++r) p1[r] = __builtin_amdgcn_exp2f(p1[r]);
;     float ps = 0;
; #pragma unroll
;     for (int r = 0; r < 16; ++r) ps += p0[r];
; #pragma unroll
;     for (int r = 0; r < 16; ++r) ps += p1[r];
;     { auto rr = __builtin_amdgcn_permlane32_swap(__float_as_uint(ps), __float_as_uint(ps), false, false);
;       ps = __uint_as_float(rr[0]) + __uint_as_float(rr[1]); }
;     l_reg = l_reg * alpha + ps;
;     ...
;     PK4(p0, 0, pa0); PK4(p0, 8, pa1); PK4(p1, 0, pa2); PK4(p1, 8, pa3);
;     ...
; }
; __device__ __forceinline__ void qkt(f32x16& p0, f32x16& p1, const bf16_t* Ks, const bf16x8* qr, int r32, int hi) {
;     p0 = f32x16{}; p1 = f32x16{};
; #pragma unroll
;     for (int d0 = 0; d0 < 8; ++d0) { int cb = (d0 * 16 + hi * 8) * 2;
;         bf16x8 b0 = *reinterpret_cast<const bf16x8*>((const char*)Ks + KSWZ(r32, cb));
;         bf16x8 b1 = *reinterpret_cast<const bf16x8*>((const char*)Ks + KSWZ(32 + r32, cb));
;         p0 = __builtin_amdgcn_mfma_f32_32x32x16_bf16(b0, qr[d0], p0, 0, 0, 0);
;         p1 = __builtin_amdgcn_mfma_f32_32x32x16_bf16(b1, qr[d0], p1, 0, 0, 0); }
; }
; __device__ __forceinline__ void attn_dense_body(const bf16_t* __restrict__ Qb, const bf16_t* __restrict__ Kh, const bf16_t* __restrict__ Vh,
;                                                 bf16_t* __restrict__ Ob, int seq, char* lds, int dry) {
;     ...
;     for (int j = 1; j + 1 < NT; j += 2) {
;         SBAR(); qkt(pB0, pB1, (bf16_t*)((char*)K_lds + oq), qr, r32, hi);
;         finishSM(pA0, pA1, alA, l_reg, pa0, pa1, pa2, pa3); SBAR();
;         SLOAD(1, (j + 2) * KVBLK); SBAR();
;         pv_d0(o, vb0 + ov, pa0, pa1, pa2, pa3); partialSM(pB0, pB1, m_reg, mnB, alB);
.LBB0_269:
	s_mov_b32 s13, s12
	s_mov_b32 s12, s8
	s_add_i32 s8, s37, 0
	v_add_u32_e32 v71, s8, v220
	ds_read_b128 v[64:67], v71 offset:49152
	ds_read_b128 v[68:71], v71 offset:57344
	v_add_u32_e32 v239, s8, v222
	ds_read_b128 v[232:235], v239 offset:49152
	ds_read_b128 v[236:239], v239 offset:57344
	v_add_u32_e32 v247, s8, v221
	ds_read_b128 v[240:243], v247 offset:49152
	ds_read_b128 v[244:247], v247 offset:57344
	s_waitcnt lgkmcnt(5)
	v_mfma_f32_32x32x16_bf16 v[80:95], v[64:67], v[126:129], 0
	v_exp_f32_e32 v163, v163
	v_exp_f32_e32 v177, v177
	v_exp_f32_e32 v164, v164
	v_exp_f32_e32 v176, v176
	s_waitcnt lgkmcnt(4)
	v_mfma_f32_32x32x16_bf16 v[64:79], v[68:71], v[126:129], 0
	v_exp_f32_e32 v165, v165
	v_exp_f32_e32 v175, v175
	v_exp_f32_e32 v171, v171
	v_exp_f32_e32 v173, v173
	s_waitcnt lgkmcnt(3)
	v_mfma_f32_32x32x16_bf16 v[80:95], v[232:235], v[122:125], v[80:95]
	v_exp_f32_e32 v172, v172
	v_exp_f32_e32 v174, v174
	v_exp_f32_e32 v167, v167
	v_exp_f32_e32 v169, v169
	s_waitcnt lgkmcnt(2)
	v_mfma_f32_32x32x16_bf16 v[64:79], v[236:239], v[122:125], v[64:79]
	v_add_u32_e32 v239, s8, v218
	ds_read_b128 v[232:235], v239 offset:49152
	ds_read_b128 v[236:239], v239 offset:57344
	v_exp_f32_e32 v168, v168
	v_exp_f32_e32 v170, v170
	v_add_f32_e32 v162, 0, v163
	v_add_f32_e32 v162, v177, v162
	s_waitcnt lgkmcnt(3)
	v_mfma_f32_32x32x16_bf16 v[80:95], v[240:243], v[118:121], v[80:95]
	v_add_f32_e32 v162, v164, v162
	v_add_f32_e32 v162, v229, v162
	v_add_f32_e32 v162, v176, v162
	v_add_f32_e32 v162, v230, v162
	s_waitcnt lgkmcnt(2)
	v_mfma_f32_32x32x16_bf16 v[64:79], v[244:247], v[118:121], v[64:79]
	v_add_u32_e32 v247, s8, v215
	ds_read_b128 v[240:243], v247 offset:49152
	ds_read_b128 v[244:247], v247 offset:57344
	v_add_f32_e32 v162, v165, v162
	v_add_f32_e32 v162, v175, v162
	v_add_f32_e32 v162, v171, v162
	v_add_f32_e32 v162, v173, v162
	s_waitcnt lgkmcnt(3)
	v_mfma_f32_32x32x16_bf16 v[80:95], v[232:235], v[114:117], v[80:95]
	v_add_f32_e32 v162, v172, v162
	v_add_f32_e32 v162, v174, v162
	v_add_f32_e32 v162, v167, v162
	v_add_f32_e32 v162, v169, v162
	s_waitcnt lgkmcnt(2)
	v_mfma_f32_32x32x16_bf16 v[64:79], v[236:239], v[114:117], v[64:79]
	v_add_u32_e32 v239, s8, v213
	ds_read_b128 v[232:235], v239 offset:49152
	ds_read_b128 v[236:239], v239 offset:57344
	v_add_f32_e32 v162, v168, v162
	v_add_f32_e32 v162, v170, v162
	v_add_f32_e32 v162, v160, v162
	v_add_f32_e32 v162, v161, v162
	s_waitcnt lgkmcnt(3)
	v_mfma_f32_32x32x16_bf16 v[80:95], v[240:243], v[110:113], v[80:95]
	v_add_f32_e32 v162, v158, v162
	v_add_f32_e32 v162, v159, v162
	v_add_f32_e32 v162, v156, v162
	v_add_f32_e32 v162, v157, v162
	s_waitcnt lgkmcnt(2)
	v_mfma_f32_32x32x16_bf16 v[64:79], v[244:247], v[110:113], v[64:79]
	v_add_u32_e32 v247, s8, v223
	ds_read_b128 v[240:243], v247 offset:49152
	ds_read_b128 v[244:247], v247 offset:57344
	v_add_f32_e32 v162, v154, v162
	v_add_f32_e32 v162, v155, v162
	v_add_f32_e32 v162, v152, v162
	v_add_f32_e32 v162, v153, v162
	s_waitcnt lgkmcnt(3)
	v_mfma_f32_32x32x16_bf16 v[80:95], v[232:235], v[106:109], v[80:95]
	v_add_f32_e32 v162, v150, v162
	v_add_f32_e32 v162, v151, v162
	v_add_f32_e32 v162, v148, v162
	v_add_f32_e32 v162, v149, v162
	s_waitcnt lgkmcnt(2)
	v_mfma_f32_32x32x16_bf16 v[64:79], v[236:239], v[106:109], v[64:79]
	v_add_u32_e32 v239, s8, v224
	ds_read_b128 v[232:235], v239 offset:49152
	ds_read_b128 v[236:239], v239 offset:57344
	v_add_f32_e32 v162, v146, v162
	v_add_f32_e32 v226, v147, v162
	v_mov_b32_e32 v227, v226
	v_cvt_pk_bf16_f32 v162, v163, v177
	s_waitcnt lgkmcnt(3)
	v_mfma_f32_32x32x16_bf16 v[80:95], v[240:243], v[102:105], v[80:95]
	v_cvt_pk_bf16_f32 v163, v164, v229
	v_cvt_pk_bf16_f32 v164, v176, v230
	v_cvt_pk_bf16_f32 v165, v165, v175
	v_cvt_pk_bf16_f32 v228, v171, v173
	s_waitcnt lgkmcnt(2)
	v_mfma_f32_32x32x16_bf16 v[64:79], v[244:247], v[102:105], v[64:79]
	v_cvt_pk_bf16_f32 v229, v172, v174
	v_cvt_pk_bf16_f32 v230, v167, v169
	v_permlane32_swap_b32_e32 v226, v227
	v_cvt_pk_bf16_f32 v231, v168, v170
	s_waitcnt lgkmcnt(1)
	v_mfma_f32_32x32x16_bf16 v[80:95], v[232:235], v[98:101], v[80:95]
	v_cvt_pk_bf16_f32 v168, v160, v161
	v_cvt_pk_bf16_f32 v169, v158, v159
	v_cvt_pk_bf16_f32 v170, v156, v157
	v_cvt_pk_bf16_f32 v171, v154, v155
	s_waitcnt lgkmcnt(0)
	v_mfma_f32_32x32x16_bf16 v[64:79], v[236:239], v[98:101], v[64:79]
	v_cvt_pk_bf16_f32 v172, v152, v153
	v_cvt_pk_bf16_f32 v173, v150, v151
	v_cvt_pk_bf16_f32 v174, v148, v149
	v_cvt_pk_bf16_f32 v175, v146, v147
	s_mov_b32 s8, 0xfffb8000
	v_add_co_u32_e32 v150, vcc, s8, v180
	s_mov_b32 s8, 0xfffd0000
	s_nop 0
	v_addc_co_u32_e32 v151, vcc, -1, v181, vcc
	v_add_co_u32_e32 v154, vcc, s8, v180
	s_nop 1
	v_addc_co_u32_e32 v155, vcc, -1, v181, vcc
	global_load_dwordx4 v[146:149], v[150:151], off
	s_nop 0
	global_load_dwordx4 v[150:153], v[150:151], off offset:-512
	s_nop 0
	global_load_dwordx4 v[158:161], v[154:155], off
	s_nop 0
	global_load_dwordx4 v[154:157], v[154:155], off offset:-512
	v_add_u32_e32 v211, s13, v212
	ds_read_b64_tr_b16 v[232:233], v211 offset:0x0
	ds_read_b64_tr_b16 v[234:235], v211 offset:0x800
	ds_read_b64_tr_b16 v[236:237], v211 offset:0x1000
	ds_read_b64_tr_b16 v[238:239], v211 offset:0x1800
	ds_read_b64_tr_b16 v[240:241], v211 offset:0x2000
	ds_read_b64_tr_b16 v[242:243], v211 offset:0x2800
	ds_read_b64_tr_b16 v[244:245], v211 offset:0x3000
	ds_read_b64_tr_b16 v[246:247], v211 offset:0x3800
	s_waitcnt lgkmcnt(0)
	s_nop 0
	v_mfma_f32_32x32x16_bf16 v[0:15], v[162:165], v[232:235], v[0:15]
	ds_read_b64_tr_b16 v[232:233], v211 offset:0x200
	ds_read_b64_tr_b16 v[234:235], v211 offset:0xa00
	s_add_i32 s14, s12, 0
	s_waitcnt vmcnt(4)
; #define SWRITE(off, i) do { *(bf16x8*)((char*)V_lds + (off) + vst0) = sv0[i];          \
;     *(bf16x8*)((char*)V_lds + (off) + vst1) = sv1[i]; int kc = sc * 2;               \
;     *(bf16x8*)((char*)K_lds + (off) + KSWZ(sr, kc)) = sk0[i];                       \
;     *(bf16x8*)((char*)K_lds + (off) + KSWZ(32 + sr, kc)) = sk1[i]; } while (0)
; #define SWAIT() asm volatile("s_waitcnt vmcnt(4)" ::: "memory")
; #define RESC(a) do { if (__any((a) < 1.f)) { if (hi == 0) al_l[r32] = (a); asm volatile("s_waitcnt lgkmcnt(0)" ::: "memory"); \
;     _Pragma("unroll") for (int d = 0; d < 4; ++d) _Pragma("unroll") for (int r = 0; r < 16; ++r) o[d][r] *= al_l[crow(r, hi)]; } } while (0)
; __device__ __forceinline__ void partialSM(f32x16& p0, f32x16& p1, float& m_reg, float& mn, float& alpha) {
;     constexpr float C = SCALE * 1.4426950408889634f;
;     float pmax = p0[0];
; #pragma unroll
;     for (int r = 1; r < 16; ++r) pmax = fmaxf(pmax, p0[r]);
; #pragma unroll
;     for (int r = 0; r < 16; ++r) pmax = fmaxf(pmax, p1[r]);
;     { auto rr = __builtin_amdgcn_permlane32_swap(__float_as_uint(pmax), __float_as_uint(pmax), false, false);
;       pmax = fmaxf(__uint_as_float(rr[0]), __uint_as_float(rr[1])); }
;     if (__builtin_expect(__all(pmax - m_reg <= THR / SCALE), 1)) { mn = m_reg; alpha = 1.f; }
;     else { mn = fmaxf(m_reg, pmax); alpha = __builtin_amdgcn_exp2f((m_reg - mn) * C); m_reg = mn; }
;     float mnC = -mn * C;
; #pragma unroll
;     for (int r = 0; r < 16; ++r) p0[r] = fmaf(p0[r], C, mnC);
; #pragma unroll
;     for (int r = 0; r < 16; ++r) p1[r] = fmaf(p1[r], C, mnC);
; __device__ __forceinline__ void attn_dense_body(const bf16_t* __restrict__ Qb, const bf16_t* __restrict__ Kh, const bf16_t* __restrict__ Vh,
;                                                 bf16_t* __restrict__ Ob, int seq, char* lds, int dry) {
;     ...
;         pv_d0(o, vb0 + ov, pa0, pa1, pa2, pa3); partialSM(pB0, pB1, m_reg, mnB, alB);
;         SWAIT(); SWRITE(ow, 0);
;         RESC(alB); __syncthreads();
	v_add_u32_e32 v253, s14, v216
	ds_write_b128 v253, v[134:137]
	v_max_f32_e32 v248, v80, v81
	v_max3_f32 v248, v248, v82, v83
	v_max3_f32 v248, v248, v84, v85
	v_max3_f32 v248, v248, v86, v87
	v_max3_f32 v248, v248, v88, v89
	v_mfma_f32_32x32x16_bf16 v[0:15], v[228:231], v[236:239], v[0:15]
	ds_read_b64_tr_b16 v[236:237], v211 offset:0x1200
	ds_read_b64_tr_b16 v[238:239], v211 offset:0x1a00
	v_add_u32_e32 v253, s14, v217
	ds_write_b128 v253, v[142:145]
	v_max3_f32 v248, v248, v90, v91
	v_max3_f32 v248, v248, v92, v93
	v_max3_f32 v248, v248, v94, v95
	v_max3_f32 v248, v248, v64, v65
	v_mfma_f32_32x32x16_bf16 v[0:15], v[168:171], v[240:243], v[0:15]
	ds_read_b64_tr_b16 v[240:241], v211 offset:0x2200
	ds_read_b64_tr_b16 v[242:243], v211 offset:0x2a00
	v_add_u32_e32 v253, s14, v214
	ds_write_b128 v253, v[138:141] offset:49152
	v_max3_f32 v248, v248, v66, v67
	v_max3_f32 v248, v248, v68, v69
	v_max3_f32 v248, v248, v70, v71
	v_max3_f32 v248, v248, v72, v73
	v_mfma_f32_32x32x16_bf16 v[0:15], v[172:175], v[244:247], v[0:15]
	ds_read_b64_tr_b16 v[244:245], v211 offset:0x3200
	ds_read_b64_tr_b16 v[246:247], v211 offset:0x3a00
	v_add_u32_e32 v253, s14, v219
	ds_write_b128 v253, v[130:133] offset:49152
	v_max3_f32 v248, v248, v74, v75
	v_max3_f32 v248, v248, v76, v77
	v_max3_f32 v248, v248, v78, v79
	v_mov_b32_e32 v249, v248
	s_waitcnt lgkmcnt(0)
	v_mfma_f32_32x32x16_bf16 v[48:63], v[162:165], v[232:235], v[48:63]
	ds_read_b64_tr_b16 v[232:233], v211 offset:0x400
	ds_read_b64_tr_b16 v[234:235], v211 offset:0xc00
	v_permlane32_swap_b32_e32 v248, v249
	v_max_f32_e32 v248, v248, v249
	v_sub_f32_e32 v249, v248, v166
	v_cmp_ge_f32_e32 vcc, s72, v249
	v_mfma_f32_32x32x16_bf16 v[48:63], v[228:231], v[236:239], v[48:63]
	ds_read_b64_tr_b16 v[236:237], v211 offset:0x1400
	ds_read_b64_tr_b16 v[238:239], v211 offset:0x1c00
	v_mfma_f32_32x32x16_bf16 v[48:63], v[168:171], v[240:243], v[48:63]
	ds_read_b64_tr_b16 v[240:241], v211 offset:0x2400
	ds_read_b64_tr_b16 v[242:243], v211 offset:0x2c00
	s_cmp_eq_u64 vcc, exec
	s_cbranch_scc0 .Lmy_rare_h1
	v_mov_b32_e32 v167, 1.0
	v_mov_b32_e32 v176, v166
	v_mul_f32_e32 v177, 0xbe0293ee, v166
.Lmy_back_h1:
	v_mfma_f32_32x32x16_bf16 v[48:63], v[172:175], v[244:247], v[48:63]
	ds_read_b64_tr_b16 v[244:245], v211 offset:0x3400
	ds_read_b64_tr_b16 v[246:247], v211 offset:0x3c00
	s_waitcnt lgkmcnt(0)
	v_mfma_f32_32x32x16_bf16 v[32:47], v[162:165], v[232:235], v[32:47]
	ds_read_b64_tr_b16 v[232:233], v211 offset:0x600
	ds_read_b64_tr_b16 v[234:235], v211 offset:0xe00
	v_fmamk_f32 v250, v92, 0x3e0293ee, v177
	v_fmamk_f32 v251, v93, 0x3e0293ee, v177
	v_fmamk_f32 v252, v94, 0x3e0293ee, v177
	v_fmamk_f32 v253, v95, 0x3e0293ee, v177
	v_mfma_f32_32x32x16_bf16 v[32:47], v[228:231], v[236:239], v[32:47]
	ds_read_b64_tr_b16 v[236:237], v211 offset:0x1600
	ds_read_b64_tr_b16 v[238:239], v211 offset:0x1e00
	v_fmamk_f32 v248, v90, 0x3e0293ee, v177
	v_fmamk_f32 v249, v91, 0x3e0293ee, v177
	v_mfma_f32_32x32x16_bf16 v[32:47], v[168:171], v[240:243], v[32:47]
	ds_read_b64_tr_b16 v[240:241], v211 offset:0x2600
	ds_read_b64_tr_b16 v[242:243], v211 offset:0x2e00
	v_exp_f32_e32 v250, v250
	v_exp_f32_e32 v251, v251
	v_exp_f32_e32 v252, v252
	v_mfma_f32_32x32x16_bf16 v[32:47], v[172:175], v[244:247], v[32:47]
	ds_read_b64_tr_b16 v[244:245], v211 offset:0x3600
	ds_read_b64_tr_b16 v[246:247], v211 offset:0x3e00
	v_exp_f32_e32 v253, v253
	v_exp_f32_e32 v248, v248
	v_exp_f32_e32 v249, v249
	s_waitcnt lgkmcnt(0)
	v_mfma_f32_32x32x16_bf16 v[16:31], v[162:165], v[232:235], v[16:31]
	v_fmamk_f32 v232, v73, 0x3e0293ee, v177
	v_fmamk_f32 v233, v74, 0x3e0293ee, v177
	v_fmamk_f32 v234, v75, 0x3e0293ee, v177
	v_fmamk_f32 v235, v76, 0x3e0293ee, v177
	v_mfma_f32_32x32x16_bf16 v[16:31], v[228:231], v[236:239], v[16:31]
	v_fmamk_f32 v238, v80, 0x3e0293ee, v177
	v_fmamk_f32 v239, v81, 0x3e0293ee, v177
	v_fmamk_f32 v236, v77, 0x3e0293ee, v177
	v_fmamk_f32 v237, v78, 0x3e0293ee, v177
	v_fmamk_f32 v230, v71, 0x3e0293ee, v177
	v_fmamk_f32 v231, v72, 0x3e0293ee, v177
	v_mfma_f32_32x32x16_bf16 v[16:31], v[168:171], v[240:243], v[16:31]
	v_fmamk_f32 v240, v82, 0x3e0293ee, v177
	v_fmamk_f32 v241, v83, 0x3e0293ee, v177
	v_fmamk_f32 v242, v84, 0x3e0293ee, v177
	v_fmamk_f32 v243, v85, 0x3e0293ee, v177
	v_fmamk_f32 v170, v79, 0x3e0293ee, v177
	v_fmamk_f32 v171, v64, 0x3e0293ee, v177
	v_mfma_f32_32x32x16_bf16 v[16:31], v[172:175], v[244:247], v[16:31]
	v_fmamk_f32 v244, v86, 0x3e0293ee, v177
	v_fmamk_f32 v245, v87, 0x3e0293ee, v177
	v_fmamk_f32 v246, v88, 0x3e0293ee, v177
	v_fmamk_f32 v247, v89, 0x3e0293ee, v177
	v_fmamk_f32 v172, v65, 0x3e0293ee, v177
	v_fmamk_f32 v173, v66, 0x3e0293ee, v177
	v_fmamk_f32 v174, v67, 0x3e0293ee, v177
	v_fmamk_f32 v175, v68, 0x3e0293ee, v177
	v_mov_b32_e32 v228, v167
	s_nop 0
	v_cmp_gt_f32_e32 vcc, 1.0, v228
	s_cbranch_vccz .LBB0_273
	s_and_saveexec_b64 s[10:11], s[6:7]
	ds_write_b32 v209, v228 offset:128
	s_or_b64 exec, exec, s[10:11]
	s_waitcnt lgkmcnt(0)
	v_add_u32_e32 v163, v179, v96
	ds_read_b128 v[80:83], v163 offset:224
	ds_read_b128 v[84:87], v163 offset:192
	ds_read_b128 v[88:91], v163 offset:160
	ds_read_b128 v[92:95], v163 offset:128
	s_waitcnt lgkmcnt(3)
	v_pk_mul_f32 v[12:13], v[12:13], v[80:81]
	s_waitcnt lgkmcnt(2)
	v_pk_mul_f32 v[8:9], v[8:9], v[84:85]
	s_waitcnt lgkmcnt(1)
	v_pk_mul_f32 v[4:5], v[4:5], v[88:89]
	v_pk_mul_f32 v[14:15], v[14:15], v[82:83]
	v_pk_mul_f32 v[10:11], v[10:11], v[86:87]
	v_pk_mul_f32 v[6:7], v[6:7], v[90:91]
	s_waitcnt lgkmcnt(0)
	v_pk_mul_f32 v[2:3], v[2:3], v[94:95]
	v_pk_mul_f32 v[0:1], v[0:1], v[92:93]
	v_pk_mul_f32 v[60:61], v[60:61], v[80:81]
	v_pk_mul_f32 v[56:57], v[56:57], v[84:85]
	v_pk_mul_f32 v[52:53], v[52:53], v[88:89]
	v_pk_mul_f32 v[62:63], v[62:63], v[82:83]
	v_pk_mul_f32 v[58:59], v[58:59], v[86:87]
	v_pk_mul_f32 v[54:55], v[54:55], v[90:91]
	v_pk_mul_f32 v[50:51], v[50:51], v[94:95]
	v_pk_mul_f32 v[48:49], v[48:49], v[92:93]
	v_pk_mul_f32 v[44:45], v[44:45], v[80:81]
	v_pk_mul_f32 v[40:41], v[40:41], v[84:85]
	v_pk_mul_f32 v[36:37], v[36:37], v[88:89]
	v_pk_mul_f32 v[46:47], v[46:47], v[82:83]
	v_pk_mul_f32 v[42:43], v[42:43], v[86:87]
	v_pk_mul_f32 v[38:39], v[38:39], v[90:91]
	v_pk_mul_f32 v[34:35], v[34:35], v[94:95]
	v_pk_mul_f32 v[32:33], v[32:33], v[92:93]
	v_pk_mul_f32 v[28:29], v[28:29], v[80:81]
	v_pk_mul_f32 v[24:25], v[24:25], v[84:85]
	v_pk_mul_f32 v[20:21], v[20:21], v[88:89]
	v_pk_mul_f32 v[30:31], v[30:31], v[82:83]
	v_pk_mul_f32 v[26:27], v[26:27], v[86:87]
	v_pk_mul_f32 v[22:23], v[22:23], v[90:91]
	v_pk_mul_f32 v[18:19], v[18:19], v[94:95]
	v_pk_mul_f32 v[16:17], v[16:17], v[92:93]

; #define SWRITE(off, i) do { *(bf16x8*)((char*)V_lds + (off) + vst0) = sv0[i];          \
;     *(bf16x8*)((char*)V_lds + (off) + vst1) = sv1[i]; int kc = sc * 2;               \
;     *(bf16x8*)((char*)K_lds + (off) + KSWZ(sr, kc)) = sk0[i];                       \
;     *(bf16x8*)((char*)K_lds + (off) + KSWZ(32 + sr, kc)) = sk1[i]; } while (0)
; #define SWAIT() asm volatile("s_waitcnt vmcnt(4)" ::: "memory")
; #define RESC(a) do { if (__any((a) < 1.f)) { if (hi == 0) al_l[r32] = (a); asm volatile("s_waitcnt lgkmcnt(0)" ::: "memory"); \
;     _Pragma("unroll") for (int d = 0; d < 4; ++d) _Pragma("unroll") for (int r = 0; r < 16; ++r) o[d][r] *= al_l[crow(r, hi)]; } } while (0)
; __device__ __forceinline__ void partialSM(f32x16& p0, f32x16& p1, float& m_reg, float& mn, float& alpha) {
;     constexpr float C = SCALE * 1.4426950408889634f;
;     float pmax = p0[0];
; #pragma unroll
;     for (int r = 1; r < 16; ++r) pmax = fmaxf(pmax, p0[r]);
; #pragma unroll
;     for (int r = 0; r < 16; ++r) pmax = fmaxf(pmax, p1[r]);
;     { auto rr = __builtin_amdgcn_permlane32_swap(__float_as_uint(pmax), __float_as_uint(pmax), false, false);
;       pmax = fmaxf(__uint_as_float(rr[0]), __uint_as_float(rr[1])); }
;     if (__builtin_expect(__all(pmax - m_reg <= THR / SCALE), 1)) { mn = m_reg; alpha = 1.f; }
;     else { mn = fmaxf(m_reg, pmax); alpha = __builtin_amdgcn_exp2f((m_reg - mn) * C); m_reg = mn; }
;     float mnC = -mn * C;
; #pragma unroll
;     for (int r = 0; r < 16; ++r) p0[r] = fmaf(p0[r], C, mnC);
; #pragma unroll
;     for (int r = 0; r < 16; ++r) p1[r] = fmaf(p1[r], C, mnC);
; __device__ __forceinline__ void attn_dense_body(const bf16_t* __restrict__ Qb, const bf16_t* __restrict__ Kh, const bf16_t* __restrict__ Vh,
;                                                 bf16_t* __restrict__ Ob, int seq, char* lds, int dry) {
;     ...
;         pv_d0(o, vb0 + ov, pa0, pa1, pa2, pa3); partialSM(pA0, pA1, m_reg, mnA, alA);
;         SWAIT(); SWRITE(ow, 1);
;         RESC(alA); __syncthreads();
.Lmy_sw_join:
	v_add_u32_e32 v194, s16, v216
	ds_write_b128 v194, v[146:149]
	v_max_f32_e32 v250, v80, v81
	v_max3_f32 v250, v250, v82, v83
	v_max3_f32 v250, v250, v84, v85
	v_max3_f32 v250, v250, v86, v87
	v_max3_f32 v250, v250, v88, v89
	v_mfma_f32_32x32x16_bf16 v[0:15], v[166:169], v[238:241], v[0:15]
	ds_read_b64_tr_b16 v[238:239], v186 offset:0x1200
	ds_read_b64_tr_b16 v[240:241], v186 offset:0x1a00
	v_add_u32_e32 v194, s16, v217
	ds_write_b128 v194, v[158:161]
	v_max3_f32 v250, v250, v90, v91
	v_max3_f32 v250, v250, v92, v93
	v_max3_f32 v250, v250, v94, v95
	v_max3_f32 v250, v250, v64, v65
	v_mfma_f32_32x32x16_bf16 v[0:15], v[170:173], v[242:245], v[0:15]
	ds_read_b64_tr_b16 v[242:243], v186 offset:0x2200
	ds_read_b64_tr_b16 v[244:245], v186 offset:0x2a00
	v_add_u32_e32 v194, s16, v214
	ds_write_b128 v194, v[150:153] offset:49152
	v_max3_f32 v250, v250, v66, v67
	v_max3_f32 v250, v250, v68, v69
	v_max3_f32 v250, v250, v70, v71
	v_max3_f32 v250, v250, v72, v73
	v_mfma_f32_32x32x16_bf16 v[0:15], v[174:177], v[246:249], v[0:15]
	ds_read_b64_tr_b16 v[246:247], v186 offset:0x3200
	ds_read_b64_tr_b16 v[248:249], v186 offset:0x3a00
	v_add_u32_e32 v194, s16, v219
	ds_write_b128 v194, v[154:157] offset:49152
	v_max3_f32 v250, v250, v74, v75
	v_max3_f32 v250, v250, v76, v77
	v_max3_f32 v250, v250, v78, v79
	v_mov_b32_e32 v251, v250
	s_waitcnt lgkmcnt(0)
	v_mfma_f32_32x32x16_bf16 v[48:63], v[162:165], v[234:237], v[48:63]
	ds_read_b64_tr_b16 v[234:235], v186 offset:0x400
	ds_read_b64_tr_b16 v[236:237], v186 offset:0xc00
	v_permlane32_swap_b32_e32 v250, v251
	v_max_f32_e32 v250, v250, v251
	v_sub_f32_e32 v251, v250, v229
	v_cmp_ge_f32_e32 vcc, s72, v251
	v_mfma_f32_32x32x16_bf16 v[48:63], v[166:169], v[238:241], v[48:63]
	ds_read_b64_tr_b16 v[238:239], v186 offset:0x1400
	ds_read_b64_tr_b16 v[240:241], v186 offset:0x1c00
	v_mfma_f32_32x32x16_bf16 v[48:63], v[170:173], v[242:245], v[48:63]
	ds_read_b64_tr_b16 v[242:243], v186 offset:0x2400
	ds_read_b64_tr_b16 v[244:245], v186 offset:0x2c00
	s_cmp_eq_u64 vcc, exec
	s_cbranch_scc0 .Lmy_rare_h2
	v_mov_b32_e32 v252, 1.0
	v_mov_b32_e32 v253, v229
	v_mul_f32_e32 v188, 0xbe0293ee, v229
.Lmy_back_h2:
	v_mfma_f32_32x32x16_bf16 v[48:63], v[174:177], v[246:249], v[48:63]
	ds_read_b64_tr_b16 v[246:247], v186 offset:0x3400
	ds_read_b64_tr_b16 v[248:249], v186 offset:0x3c00
	s_waitcnt lgkmcnt(0)
	v_mfma_f32_32x32x16_bf16 v[32:47], v[162:165], v[234:237], v[32:47]
	ds_read_b64_tr_b16 v[234:235], v186 offset:0x600
	ds_read_b64_tr_b16 v[236:237], v186 offset:0xe00
	v_fmamk_f32 v230, v85, 0x3e0293ee, v188
	v_fmamk_f32 v229, v83, 0x3e0293ee, v188
	v_fmamk_f32 v160, v64, 0x3e0293ee, v188
	v_fmamk_f32 v161, v65, 0x3e0293ee, v188
	v_fmamk_f32 v158, v66, 0x3e0293ee, v188
	v_mfma_f32_32x32x16_bf16 v[32:47], v[166:169], v[238:241], v[32:47]
	ds_read_b64_tr_b16 v[238:239], v186 offset:0x1600
	ds_read_b64_tr_b16 v[240:241], v186 offset:0x1e00
	v_fmamk_f32 v159, v67, 0x3e0293ee, v188
	v_fmamk_f32 v156, v68, 0x3e0293ee, v188
	v_fmamk_f32 v157, v69, 0x3e0293ee, v188
	v_fmamk_f32 v154, v70, 0x3e0293ee, v188
	v_fmamk_f32 v155, v71, 0x3e0293ee, v188
	v_exp_f32_e32 v230, v230
	v_exp_f32_e32 v229, v229
	v_mfma_f32_32x32x16_bf16 v[32:47], v[170:173], v[242:245], v[32:47]
	ds_read_b64_tr_b16 v[242:243], v186 offset:0x2600
	ds_read_b64_tr_b16 v[244:245], v186 offset:0x2e00
	v_fmamk_f32 v152, v72, 0x3e0293ee, v188
	v_fmamk_f32 v153, v73, 0x3e0293ee, v188
	v_fmamk_f32 v150, v74, 0x3e0293ee, v188
	v_fmamk_f32 v151, v75, 0x3e0293ee, v188
	v_fmamk_f32 v148, v76, 0x3e0293ee, v188
	v_exp_f32_e32 v160, v160
	v_exp_f32_e32 v161, v161
	v_mfma_f32_32x32x16_bf16 v[32:47], v[174:177], v[246:249], v[32:47]
	ds_read_b64_tr_b16 v[246:247], v186 offset:0x3600
	ds_read_b64_tr_b16 v[248:249], v186 offset:0x3e00
	v_fmamk_f32 v149, v77, 0x3e0293ee, v188
	v_fmamk_f32 v146, v78, 0x3e0293ee, v188
	v_fmamk_f32 v147, v79, 0x3e0293ee, v188
	v_exp_f32_e32 v158, v158
	v_exp_f32_e32 v159, v159
	v_exp_f32_e32 v156, v156
	s_waitcnt lgkmcnt(0)
	v_mfma_f32_32x32x16_bf16 v[16:31], v[162:165], v[234:237], v[16:31]
	v_fmamk_f32 v163, v80, 0x3e0293ee, v188
	v_fmamk_f32 v164, v82, 0x3e0293ee, v188
	v_fmamk_f32 v165, v86, 0x3e0293ee, v188
	v_exp_f32_e32 v157, v157
	v_exp_f32_e32 v154, v154
	v_exp_f32_e32 v155, v155
	v_mfma_f32_32x32x16_bf16 v[16:31], v[166:169], v[238:241], v[16:31]
	v_fmamk_f32 v167, v92, 0x3e0293ee, v188
	v_fmamk_f32 v169, v93, 0x3e0293ee, v188
	v_fmamk_f32 v168, v94, 0x3e0293ee, v188
	v_exp_f32_e32 v152, v152
	v_exp_f32_e32 v153, v153
	v_exp_f32_e32 v150, v150
	v_mfma_f32_32x32x16_bf16 v[16:31], v[170:173], v[242:245], v[16:31]
	v_fmamk_f32 v171, v88, 0x3e0293ee, v188
	v_fmamk_f32 v173, v89, 0x3e0293ee, v188
	v_fmamk_f32 v172, v90, 0x3e0293ee, v188
	v_fmamk_f32 v170, v95, 0x3e0293ee, v188
	v_exp_f32_e32 v151, v151
	v_exp_f32_e32 v148, v148
	v_exp_f32_e32 v149, v149
	v_mfma_f32_32x32x16_bf16 v[16:31], v[174:177], v[246:249], v[16:31]
	v_fmamk_f32 v177, v81, 0x3e0293ee, v188
	v_fmamk_f32 v176, v84, 0x3e0293ee, v188
	v_fmamk_f32 v175, v87, 0x3e0293ee, v188
	v_fmamk_f32 v174, v91, 0x3e0293ee, v188
	v_exp_f32_e32 v146, v146
	v_exp_f32_e32 v147, v147
	v_mov_b32_e32 v162, v252
	s_nop 0
	v_cmp_gt_f32_e32 vcc, 1.0, v162
	s_cbranch_vccz .LBB0_279
	s_and_saveexec_b64 s[14:15], s[6:7]
	ds_write_b32 v209, v162 offset:128
	s_or_b64 exec, exec, s[14:15]
	s_waitcnt lgkmcnt(0)
	v_add_u32_e32 v250, v179, v96
	ds_read_b128 v[80:83], v250 offset:224
	ds_read_b128 v[84:87], v250 offset:192
	ds_read_b128 v[88:91], v250 offset:160
	ds_read_b128 v[92:95], v250 offset:128
	s_waitcnt lgkmcnt(3)
	v_pk_mul_f32 v[12:13], v[12:13], v[80:81]
	s_waitcnt lgkmcnt(2)
	v_pk_mul_f32 v[8:9], v[8:9], v[84:85]
	s_waitcnt lgkmcnt(1)
	v_pk_mul_f32 v[4:5], v[4:5], v[88:89]
	v_pk_mul_f32 v[14:15], v[14:15], v[82:83]
	v_pk_mul_f32 v[10:11], v[10:11], v[86:87]
	v_pk_mul_f32 v[6:7], v[6:7], v[90:91]
	s_waitcnt lgkmcnt(0)
	v_pk_mul_f32 v[2:3], v[2:3], v[94:95]
	v_pk_mul_f32 v[0:1], v[0:1], v[92:93]
	v_pk_mul_f32 v[60:61], v[60:61], v[80:81]
	v_pk_mul_f32 v[56:57], v[56:57], v[84:85]
	v_pk_mul_f32 v[52:53], v[52:53], v[88:89]
	v_pk_mul_f32 v[62:63], v[62:63], v[82:83]
	v_pk_mul_f32 v[58:59], v[58:59], v[86:87]
	v_pk_mul_f32 v[54:55], v[54:55], v[90:91]
	v_pk_mul_f32 v[50:51], v[50:51], v[94:95]
	v_pk_mul_f32 v[48:49], v[48:49], v[92:93]
	v_pk_mul_f32 v[44:45], v[44:45], v[80:81]
	v_pk_mul_f32 v[40:41], v[40:41], v[84:85]
	v_pk_mul_f32 v[36:37], v[36:37], v[88:89]
	v_pk_mul_f32 v[46:47], v[46:47], v[82:83]
	v_pk_mul_f32 v[42:43], v[42:43], v[86:87]
	v_pk_mul_f32 v[38:39], v[38:39], v[90:91]
	v_pk_mul_f32 v[34:35], v[34:35], v[94:95]
	v_pk_mul_f32 v[32:33], v[32:33], v[92:93]
	v_pk_mul_f32 v[28:29], v[28:29], v[80:81]
	v_pk_mul_f32 v[24:25], v[24:25], v[84:85]
	v_pk_mul_f32 v[20:21], v[20:21], v[88:89]
	v_pk_mul_f32 v[30:31], v[30:31], v[82:83]
	v_pk_mul_f32 v[26:27], v[26:27], v[86:87]
	v_pk_mul_f32 v[22:23], v[22:23], v[90:91]
	v_pk_mul_f32 v[18:19], v[18:19], v[94:95]
	v_pk_mul_f32 v[16:17], v[16:17], v[92:93]

; __device__ __forceinline__ void partialSM(f32x16& p0, f32x16& p1, float& m_reg, float& mn, float& alpha) {
;     ...
;     if (__builtin_expect(__all(pmax - m_reg <= THR / SCALE), 1)) { mn = m_reg; alpha = 1.f; }
;     else { mn = fmaxf(m_reg, pmax); alpha = __builtin_amdgcn_exp2f((m_reg - mn) * C); m_reg = mn; }
.Lmy_rare_h1:
	v_max_f32_e32 v248, v166, v248
	v_sub_f32_e32 v249, v166, v248
	v_mul_f32_e32 v249, 0x3e0293ee, v249
	v_exp_f32_e32 v249, v249
	s_nop 0
	v_mov_b32_e32 v167, v249
	v_mov_b32_e32 v176, v248
	v_mul_f32_e32 v177, 0xbe0293ee, v176
	s_branch .Lmy_back_h1
.Lmy_rare_h2:
	v_max_f32_e32 v250, v229, v250
	v_sub_f32_e32 v251, v229, v250
	v_mul_f32_e32 v251, 0x3e0293ee, v251
	v_exp_f32_e32 v251, v251
	s_nop 0
	v_mov_b32_e32 v252, v251
	v_mov_b32_e32 v253, v250
	v_mul_f32_e32 v188, 0xbe0293ee, v253
	s_branch .Lmy_back_h2
